# merge phase rewritten by hand: one K-loop computes the three gate GEMMs from a shared H tile (A fetched once, 2-stage 32KB LDS ring), gated sum in epilogue
# speedup vs baseline: 1.0943x; 1.0278x over previous
.LBB0_189:
	s_lshr_b32 s1, s24, 3
	s_and_b32 s0, s24, 7
	s_and_b32 s1, s1, 0x1fffff8
	s_or_b32 s0, s1, s0
	s_lshl_b32 s0, s0, 7
	s_lshl_b32 s1, s24, 4
	s_and_b32 s25, s1, 0x380
	s_lshl_b32 s2, s0, 11
	s_add_u32 s8, s15, s2
	s_addc_u32 s9, s16, 0
	s_lshl_b32 s1, s25, 11
	s_add_u32 s10, s17, s1
	s_addc_u32 s11, s18, 0
	s_add_u32 s12, s10, 0x200000
	s_addc_u32 s13, s11, 0
	s_add_u32 s36, s10, 0x400000
	s_addc_u32 s37, s11, 0
	s_lshl_b32 s1, s25, 1
	s_add_u32 s2, s2, s1
	v_lshrrev_b32_e32 v0, 2, v196
	v_and_b32_e32 v0, 12, v0
	v_lshrrev_b32_e64 v0, v0, s57
	v_xor_b32_e32 v0, v0, v196
	v_and_b32_e32 v0, 3, v0
	v_lshlrev_b32_e32 v0, 4, v0
	v_lshrrev_b32_e32 v194, 2, v196
	v_lshl_add_u32 v194, v194, 11, v0
	v_add_u32_e32 v195, 0x20000, v194
	v_and_b32_e32 v213, 15, v196
	v_and_b32_e32 v215, 12, v213
	v_lshrrev_b32_e64 v215, v215, s57
	v_and_b32_e32 v215, 3, v215
	v_bfe_u32 v220, v196, 4, 2
	v_xor_b32_e32 v215, v215, v220
	v_lshlrev_b32_e32 v215, 4, v215
	v_lshl_add_u32 v215, v213, 6, v215
	v_lshrrev_b32_e32 v213, 7, v196
	v_lshl_add_u32 v213, v213, 12, v215
	v_bfe_u32 v214, v196, 6, 1
	v_lshl_add_u32 v214, v214, 12, v215
	v_readfirstlane_b32 s26, v196
	s_lshl_b32 s26, s26, 4
	s_mov_b32 m0, s26
	s_nop 0
	global_load_lds_dwordx4 v194, s[8:9]
	s_add_i32 m0, s26, 0x1000
	s_nop 0
	global_load_lds_dwordx4 v195, s[8:9]
	s_add_i32 m0, s26, 0x2000
	s_nop 0
	global_load_lds_dwordx4 v194, s[10:11]
	s_add_i32 m0, s26, 0x3000
	s_nop 0
	global_load_lds_dwordx4 v195, s[10:11]
	s_add_i32 m0, s26, 0x4000
	s_nop 0
	global_load_lds_dwordx4 v194, s[12:13]
	s_add_i32 m0, s26, 0x5000
	s_nop 0
	global_load_lds_dwordx4 v195, s[12:13]
	s_add_i32 m0, s26, 0x6000
	s_nop 0
	global_load_lds_dwordx4 v194, s[36:37]
	s_add_i32 m0, s26, 0x7000
	s_nop 0
	global_load_lds_dwordx4 v195, s[36:37]
	v_add_u32_e32 v194, 64, v194
	v_add_u32_e32 v195, 64, v195
	v_mov_b32_e32 v2, 0
	v_mov_b32_e32 v3, 0
	v_mov_b32_e32 v4, 0
	v_mov_b32_e32 v5, 0
	v_mov_b32_e32 v6, 0
	v_mov_b32_e32 v7, 0
	v_mov_b32_e32 v8, 0
	v_mov_b32_e32 v9, 0
	v_mov_b32_e32 v10, 0
	v_mov_b32_e32 v11, 0
	v_mov_b32_e32 v12, 0
	v_mov_b32_e32 v13, 0
	v_mov_b32_e32 v14, 0
	v_mov_b32_e32 v15, 0
	v_mov_b32_e32 v16, 0
	v_mov_b32_e32 v17, 0
	v_mov_b32_e32 v18, 0
	v_mov_b32_e32 v19, 0
	v_mov_b32_e32 v20, 0
	v_mov_b32_e32 v21, 0
	v_mov_b32_e32 v22, 0
	v_mov_b32_e32 v23, 0
	v_mov_b32_e32 v24, 0
	v_mov_b32_e32 v25, 0
	v_mov_b32_e32 v26, 0
	v_mov_b32_e32 v27, 0
	v_mov_b32_e32 v28, 0
	v_mov_b32_e32 v29, 0
	v_mov_b32_e32 v30, 0
	v_mov_b32_e32 v31, 0
	v_mov_b32_e32 v32, 0
	v_mov_b32_e32 v33, 0
	v_mov_b32_e32 v34, 0
	v_mov_b32_e32 v35, 0
	v_mov_b32_e32 v36, 0
	v_mov_b32_e32 v37, 0
	v_mov_b32_e32 v38, 0
	v_mov_b32_e32 v39, 0
	v_mov_b32_e32 v40, 0
	v_mov_b32_e32 v41, 0
	v_mov_b32_e32 v42, 0
	v_mov_b32_e32 v43, 0
	v_mov_b32_e32 v44, 0
	v_mov_b32_e32 v45, 0
	v_mov_b32_e32 v46, 0
	v_mov_b32_e32 v47, 0
	v_mov_b32_e32 v48, 0
	v_mov_b32_e32 v49, 0
	v_mov_b32_e32 v50, 0
	v_mov_b32_e32 v51, 0
	v_mov_b32_e32 v52, 0
	v_mov_b32_e32 v53, 0
	v_mov_b32_e32 v54, 0
	v_mov_b32_e32 v55, 0
	v_mov_b32_e32 v56, 0
	v_mov_b32_e32 v57, 0
	v_mov_b32_e32 v58, 0
	v_mov_b32_e32 v59, 0
	v_mov_b32_e32 v60, 0
	v_mov_b32_e32 v61, 0
	v_mov_b32_e32 v62, 0
	v_mov_b32_e32 v63, 0
	v_mov_b32_e32 v64, 0
	v_mov_b32_e32 v65, 0
	v_mov_b32_e32 v66, 0
	v_mov_b32_e32 v67, 0
	v_mov_b32_e32 v68, 0
	v_mov_b32_e32 v69, 0
	v_mov_b32_e32 v70, 0
	v_mov_b32_e32 v71, 0
	v_mov_b32_e32 v72, 0
	v_mov_b32_e32 v73, 0
	v_mov_b32_e32 v74, 0
	v_mov_b32_e32 v75, 0
	v_mov_b32_e32 v76, 0
	v_mov_b32_e32 v77, 0
	v_mov_b32_e32 v78, 0
	v_mov_b32_e32 v79, 0
	v_mov_b32_e32 v80, 0
	v_mov_b32_e32 v81, 0
	v_mov_b32_e32 v82, 0
	v_mov_b32_e32 v83, 0
	v_mov_b32_e32 v84, 0
	v_mov_b32_e32 v85, 0
	v_mov_b32_e32 v86, 0
	v_mov_b32_e32 v87, 0
	v_mov_b32_e32 v88, 0
	v_mov_b32_e32 v89, 0
	v_mov_b32_e32 v90, 0
	v_mov_b32_e32 v91, 0
	v_mov_b32_e32 v92, 0
	v_mov_b32_e32 v93, 0
	v_mov_b32_e32 v94, 0
	v_mov_b32_e32 v95, 0
	v_mov_b32_e32 v96, 0
	v_mov_b32_e32 v97, 0
	v_mov_b32_e32 v98, 0
	v_mov_b32_e32 v99, 0
	v_mov_b32_e32 v100, 0
	v_mov_b32_e32 v101, 0
	v_mov_b32_e32 v102, 0
	v_mov_b32_e32 v103, 0
	v_mov_b32_e32 v104, 0
	v_mov_b32_e32 v105, 0
	v_mov_b32_e32 v106, 0
	v_mov_b32_e32 v107, 0
	v_mov_b32_e32 v108, 0
	v_mov_b32_e32 v109, 0
	v_mov_b32_e32 v110, 0
	v_mov_b32_e32 v111, 0
	v_mov_b32_e32 v112, 0
	v_mov_b32_e32 v113, 0
	v_mov_b32_e32 v114, 0
	v_mov_b32_e32 v115, 0
	v_mov_b32_e32 v116, 0
	v_mov_b32_e32 v117, 0
	v_mov_b32_e32 v118, 0
	v_mov_b32_e32 v119, 0
	v_mov_b32_e32 v120, 0
	v_mov_b32_e32 v121, 0
	v_mov_b32_e32 v122, 0
	v_mov_b32_e32 v123, 0
	v_mov_b32_e32 v124, 0
	v_mov_b32_e32 v125, 0
	v_mov_b32_e32 v126, 0
	v_mov_b32_e32 v127, 0
	v_mov_b32_e32 v128, 0
	v_mov_b32_e32 v129, 0
	v_mov_b32_e32 v130, 0
	v_mov_b32_e32 v131, 0
	v_mov_b32_e32 v132, 0
	v_mov_b32_e32 v133, 0
	v_mov_b32_e32 v134, 0
	v_mov_b32_e32 v135, 0
	v_mov_b32_e32 v136, 0
	v_mov_b32_e32 v137, 0
	v_mov_b32_e32 v138, 0
	v_mov_b32_e32 v139, 0
	v_mov_b32_e32 v140, 0
	v_mov_b32_e32 v141, 0
	v_mov_b32_e32 v142, 0
	v_mov_b32_e32 v143, 0
	v_mov_b32_e32 v144, 0
	v_mov_b32_e32 v145, 0
	v_mov_b32_e32 v146, 0
	v_mov_b32_e32 v147, 0
	v_mov_b32_e32 v148, 0
	v_mov_b32_e32 v149, 0
	v_mov_b32_e32 v150, 0
	v_mov_b32_e32 v151, 0
	v_mov_b32_e32 v152, 0
	v_mov_b32_e32 v153, 0
	v_mov_b32_e32 v154, 0
	v_mov_b32_e32 v155, 0
	v_mov_b32_e32 v156, 0
	v_mov_b32_e32 v157, 0
	v_mov_b32_e32 v158, 0
	v_mov_b32_e32 v159, 0
	v_mov_b32_e32 v160, 0
	v_mov_b32_e32 v161, 0
	v_mov_b32_e32 v162, 0
	v_mov_b32_e32 v163, 0
	v_mov_b32_e32 v164, 0
	v_mov_b32_e32 v165, 0
	v_mov_b32_e32 v166, 0
	v_mov_b32_e32 v167, 0
	v_mov_b32_e32 v168, 0
	v_mov_b32_e32 v169, 0
	v_mov_b32_e32 v170, 0
	v_mov_b32_e32 v171, 0
	v_mov_b32_e32 v172, 0
	v_mov_b32_e32 v173, 0
	v_mov_b32_e32 v174, 0
	v_mov_b32_e32 v175, 0
	v_mov_b32_e32 v176, 0
	v_mov_b32_e32 v177, 0
	v_mov_b32_e32 v178, 0
	v_mov_b32_e32 v179, 0
	v_mov_b32_e32 v180, 0
	v_mov_b32_e32 v181, 0
	v_mov_b32_e32 v182, 0
	v_mov_b32_e32 v183, 0
	v_mov_b32_e32 v184, 0
	v_mov_b32_e32 v185, 0
	v_mov_b32_e32 v186, 0
	v_mov_b32_e32 v187, 0
	v_mov_b32_e32 v188, 0
	v_mov_b32_e32 v189, 0
	v_mov_b32_e32 v190, 0
	v_mov_b32_e32 v191, 0
	v_mov_b32_e32 v192, 0
	v_mov_b32_e32 v193, 0
	s_mov_b32 s27, 16
.Lmg_loop:
	s_waitcnt vmcnt(0)
	s_barrier
	s_add_i32 m0, s26, 0x8000
	s_nop 0
	global_load_lds_dwordx4 v194, s[8:9]
	s_add_i32 m0, s26, 0x9000
	s_nop 0
	global_load_lds_dwordx4 v195, s[8:9]
	s_add_i32 m0, s26, 0xa000
	s_nop 0
	global_load_lds_dwordx4 v194, s[10:11]
	s_add_i32 m0, s26, 0xb000
	s_nop 0
	global_load_lds_dwordx4 v195, s[10:11]
	s_add_i32 m0, s26, 0xc000
	s_nop 0
	global_load_lds_dwordx4 v194, s[12:13]
	s_add_i32 m0, s26, 0xd000
	s_nop 0
	global_load_lds_dwordx4 v195, s[12:13]
	s_add_i32 m0, s26, 0xe000
	s_nop 0
	global_load_lds_dwordx4 v194, s[36:37]
	s_add_i32 m0, s26, 0xf000
	s_nop 0
	global_load_lds_dwordx4 v195, s[36:37]
	v_add_u32_e32 v194, 64, v194
	v_add_u32_e32 v195, 64, v195
	ds_read_b128 v[228:231], v213 offset:0
	ds_read_b128 v[232:235], v213 offset:1024
	ds_read_b128 v[236:239], v213 offset:2048
	ds_read_b128 v[240:243], v213 offset:3072
	ds_read_b128 v[244:247], v214 offset:8192
	ds_read_b128 v[248:251], v214 offset:9216
	ds_read_b128 v[252:255], v214 offset:10240
	ds_read_b128 v[216:219], v214 offset:11264
	s_waitcnt lgkmcnt(3)
	v_mfma_f32_16x16x32_bf16 v[2:5], v[244:247], v[228:231], v[2:5]
	v_mfma_f32_16x16x32_bf16 v[18:21], v[244:247], v[232:235], v[18:21]
	v_mfma_f32_16x16x32_bf16 v[34:37], v[244:247], v[236:239], v[34:37]
	v_mfma_f32_16x16x32_bf16 v[50:53], v[244:247], v[240:243], v[50:53]
	ds_read_b128 v[244:247], v214 offset:16384
	s_waitcnt lgkmcnt(3)
	v_mfma_f32_16x16x32_bf16 v[6:9], v[248:251], v[228:231], v[6:9]
	v_mfma_f32_16x16x32_bf16 v[22:25], v[248:251], v[232:235], v[22:25]
	v_mfma_f32_16x16x32_bf16 v[38:41], v[248:251], v[236:239], v[38:41]
	v_mfma_f32_16x16x32_bf16 v[54:57], v[248:251], v[240:243], v[54:57]
	ds_read_b128 v[248:251], v214 offset:17408
	s_waitcnt lgkmcnt(3)
	v_mfma_f32_16x16x32_bf16 v[10:13], v[252:255], v[228:231], v[10:13]
	v_mfma_f32_16x16x32_bf16 v[26:29], v[252:255], v[232:235], v[26:29]
	v_mfma_f32_16x16x32_bf16 v[42:45], v[252:255], v[236:239], v[42:45]
	v_mfma_f32_16x16x32_bf16 v[58:61], v[252:255], v[240:243], v[58:61]
	ds_read_b128 v[252:255], v214 offset:18432
	s_waitcnt lgkmcnt(3)
	v_mfma_f32_16x16x32_bf16 v[14:17], v[216:219], v[228:231], v[14:17]
	v_mfma_f32_16x16x32_bf16 v[30:33], v[216:219], v[232:235], v[30:33]
	v_mfma_f32_16x16x32_bf16 v[46:49], v[216:219], v[236:239], v[46:49]
	v_mfma_f32_16x16x32_bf16 v[62:65], v[216:219], v[240:243], v[62:65]
	ds_read_b128 v[216:219], v214 offset:19456
	s_waitcnt lgkmcnt(3)
	v_mfma_f32_16x16x32_bf16 v[66:69], v[244:247], v[228:231], v[66:69]
	v_mfma_f32_16x16x32_bf16 v[82:85], v[244:247], v[232:235], v[82:85]
	v_mfma_f32_16x16x32_bf16 v[98:101], v[244:247], v[236:239], v[98:101]
	v_mfma_f32_16x16x32_bf16 v[114:117], v[244:247], v[240:243], v[114:117]
	ds_read_b128 v[244:247], v214 offset:24576
	s_waitcnt lgkmcnt(3)
	v_mfma_f32_16x16x32_bf16 v[70:73], v[248:251], v[228:231], v[70:73]
	v_mfma_f32_16x16x32_bf16 v[86:89], v[248:251], v[232:235], v[86:89]
	v_mfma_f32_16x16x32_bf16 v[102:105], v[248:251], v[236:239], v[102:105]
	v_mfma_f32_16x16x32_bf16 v[118:121], v[248:251], v[240:243], v[118:121]
	ds_read_b128 v[248:251], v214 offset:25600
	s_waitcnt lgkmcnt(3)
	v_mfma_f32_16x16x32_bf16 v[74:77], v[252:255], v[228:231], v[74:77]
	v_mfma_f32_16x16x32_bf16 v[90:93], v[252:255], v[232:235], v[90:93]
	v_mfma_f32_16x16x32_bf16 v[106:109], v[252:255], v[236:239], v[106:109]
	v_mfma_f32_16x16x32_bf16 v[122:125], v[252:255], v[240:243], v[122:125]
	ds_read_b128 v[252:255], v214 offset:26624
	s_waitcnt lgkmcnt(3)
	v_mfma_f32_16x16x32_bf16 v[78:81], v[216:219], v[228:231], v[78:81]
	v_mfma_f32_16x16x32_bf16 v[94:97], v[216:219], v[232:235], v[94:97]
	v_mfma_f32_16x16x32_bf16 v[110:113], v[216:219], v[236:239], v[110:113]
	v_mfma_f32_16x16x32_bf16 v[126:129], v[216:219], v[240:243], v[126:129]
	ds_read_b128 v[216:219], v214 offset:27648
	s_waitcnt lgkmcnt(3)
	v_mfma_f32_16x16x32_bf16 v[130:133], v[244:247], v[228:231], v[130:133]
	v_mfma_f32_16x16x32_bf16 v[146:149], v[244:247], v[232:235], v[146:149]
	v_mfma_f32_16x16x32_bf16 v[162:165], v[244:247], v[236:239], v[162:165]
	v_mfma_f32_16x16x32_bf16 v[178:181], v[244:247], v[240:243], v[178:181]
	s_waitcnt lgkmcnt(2)
	v_mfma_f32_16x16x32_bf16 v[134:137], v[248:251], v[228:231], v[134:137]
	v_mfma_f32_16x16x32_bf16 v[150:153], v[248:251], v[232:235], v[150:153]
	v_mfma_f32_16x16x32_bf16 v[166:169], v[248:251], v[236:239], v[166:169]
	v_mfma_f32_16x16x32_bf16 v[182:185], v[248:251], v[240:243], v[182:185]
	s_waitcnt lgkmcnt(1)
	v_mfma_f32_16x16x32_bf16 v[138:141], v[252:255], v[228:231], v[138:141]
	v_mfma_f32_16x16x32_bf16 v[154:157], v[252:255], v[232:235], v[154:157]
	v_mfma_f32_16x16x32_bf16 v[170:173], v[252:255], v[236:239], v[170:173]
	v_mfma_f32_16x16x32_bf16 v[186:189], v[252:255], v[240:243], v[186:189]
	s_waitcnt lgkmcnt(0)
	v_mfma_f32_16x16x32_bf16 v[142:145], v[216:219], v[228:231], v[142:145]
	v_mfma_f32_16x16x32_bf16 v[158:161], v[216:219], v[232:235], v[158:161]
	v_mfma_f32_16x16x32_bf16 v[174:177], v[216:219], v[236:239], v[174:177]
	v_mfma_f32_16x16x32_bf16 v[190:193], v[216:219], v[240:243], v[190:193]
	s_waitcnt vmcnt(0)
	s_barrier
	s_cmp_eq_u32 s27, 1
	s_cbranch_scc1 .Lmg_skip
	s_mov_b32 m0, s26
	s_nop 0
	global_load_lds_dwordx4 v194, s[8:9]
	s_add_i32 m0, s26, 0x1000
	s_nop 0
	global_load_lds_dwordx4 v195, s[8:9]
	s_add_i32 m0, s26, 0x2000
	s_nop 0
	global_load_lds_dwordx4 v194, s[10:11]
	s_add_i32 m0, s26, 0x3000
	s_nop 0
	global_load_lds_dwordx4 v195, s[10:11]
	s_add_i32 m0, s26, 0x4000
	s_nop 0
	global_load_lds_dwordx4 v194, s[12:13]
	s_add_i32 m0, s26, 0x5000
	s_nop 0
	global_load_lds_dwordx4 v195, s[12:13]
	s_add_i32 m0, s26, 0x6000
	s_nop 0
	global_load_lds_dwordx4 v194, s[36:37]
	s_add_i32 m0, s26, 0x7000
	s_nop 0
	global_load_lds_dwordx4 v195, s[36:37]
	v_add_u32_e32 v194, 64, v194
	v_add_u32_e32 v195, 64, v195
.Lmg_skip:
	ds_read_b128 v[228:231], v213 offset:32768
	ds_read_b128 v[232:235], v213 offset:33792
	ds_read_b128 v[236:239], v213 offset:34816
	ds_read_b128 v[240:243], v213 offset:35840
	ds_read_b128 v[244:247], v214 offset:40960
	ds_read_b128 v[248:251], v214 offset:41984
	ds_read_b128 v[252:255], v214 offset:43008
	ds_read_b128 v[216:219], v214 offset:44032
	s_waitcnt lgkmcnt(3)
	v_mfma_f32_16x16x32_bf16 v[2:5], v[244:247], v[228:231], v[2:5]
	v_mfma_f32_16x16x32_bf16 v[18:21], v[244:247], v[232:235], v[18:21]
	v_mfma_f32_16x16x32_bf16 v[34:37], v[244:247], v[236:239], v[34:37]
	v_mfma_f32_16x16x32_bf16 v[50:53], v[244:247], v[240:243], v[50:53]
	ds_read_b128 v[244:247], v214 offset:49152
	s_waitcnt lgkmcnt(3)
	v_mfma_f32_16x16x32_bf16 v[6:9], v[248:251], v[228:231], v[6:9]
	v_mfma_f32_16x16x32_bf16 v[22:25], v[248:251], v[232:235], v[22:25]
	v_mfma_f32_16x16x32_bf16 v[38:41], v[248:251], v[236:239], v[38:41]
	v_mfma_f32_16x16x32_bf16 v[54:57], v[248:251], v[240:243], v[54:57]
	ds_read_b128 v[248:251], v214 offset:50176
	s_waitcnt lgkmcnt(3)
	v_mfma_f32_16x16x32_bf16 v[10:13], v[252:255], v[228:231], v[10:13]
	v_mfma_f32_16x16x32_bf16 v[26:29], v[252:255], v[232:235], v[26:29]
	v_mfma_f32_16x16x32_bf16 v[42:45], v[252:255], v[236:239], v[42:45]
	v_mfma_f32_16x16x32_bf16 v[58:61], v[252:255], v[240:243], v[58:61]
	ds_read_b128 v[252:255], v214 offset:51200
	s_waitcnt lgkmcnt(3)
	v_mfma_f32_16x16x32_bf16 v[14:17], v[216:219], v[228:231], v[14:17]
	v_mfma_f32_16x16x32_bf16 v[30:33], v[216:219], v[232:235], v[30:33]
	v_mfma_f32_16x16x32_bf16 v[46:49], v[216:219], v[236:239], v[46:49]
	v_mfma_f32_16x16x32_bf16 v[62:65], v[216:219], v[240:243], v[62:65]
	ds_read_b128 v[216:219], v214 offset:52224
	s_waitcnt lgkmcnt(3)
	v_mfma_f32_16x16x32_bf16 v[66:69], v[244:247], v[228:231], v[66:69]
	v_mfma_f32_16x16x32_bf16 v[82:85], v[244:247], v[232:235], v[82:85]
	v_mfma_f32_16x16x32_bf16 v[98:101], v[244:247], v[236:239], v[98:101]
	v_mfma_f32_16x16x32_bf16 v[114:117], v[244:247], v[240:243], v[114:117]
	ds_read_b128 v[244:247], v214 offset:57344
	s_waitcnt lgkmcnt(3)
	v_mfma_f32_16x16x32_bf16 v[70:73], v[248:251], v[228:231], v[70:73]
	v_mfma_f32_16x16x32_bf16 v[86:89], v[248:251], v[232:235], v[86:89]
	v_mfma_f32_16x16x32_bf16 v[102:105], v[248:251], v[236:239], v[102:105]
	v_mfma_f32_16x16x32_bf16 v[118:121], v[248:251], v[240:243], v[118:121]
	ds_read_b128 v[248:251], v214 offset:58368
	s_waitcnt lgkmcnt(3)
	v_mfma_f32_16x16x32_bf16 v[74:77], v[252:255], v[228:231], v[74:77]
	v_mfma_f32_16x16x32_bf16 v[90:93], v[252:255], v[232:235], v[90:93]
	v_mfma_f32_16x16x32_bf16 v[106:109], v[252:255], v[236:239], v[106:109]
	v_mfma_f32_16x16x32_bf16 v[122:125], v[252:255], v[240:243], v[122:125]
	ds_read_b128 v[252:255], v214 offset:59392
	s_waitcnt lgkmcnt(3)
	v_mfma_f32_16x16x32_bf16 v[78:81], v[216:219], v[228:231], v[78:81]
	v_mfma_f32_16x16x32_bf16 v[94:97], v[216:219], v[232:235], v[94:97]
	v_mfma_f32_16x16x32_bf16 v[110:113], v[216:219], v[236:239], v[110:113]
	v_mfma_f32_16x16x32_bf16 v[126:129], v[216:219], v[240:243], v[126:129]
	ds_read_b128 v[216:219], v214 offset:60416
	s_waitcnt lgkmcnt(3)
	v_mfma_f32_16x16x32_bf16 v[130:133], v[244:247], v[228:231], v[130:133]
	v_mfma_f32_16x16x32_bf16 v[146:149], v[244:247], v[232:235], v[146:149]
	v_mfma_f32_16x16x32_bf16 v[162:165], v[244:247], v[236:239], v[162:165]
	v_mfma_f32_16x16x32_bf16 v[178:181], v[244:247], v[240:243], v[178:181]
	s_waitcnt lgkmcnt(2)
	v_mfma_f32_16x16x32_bf16 v[134:137], v[248:251], v[228:231], v[134:137]
	v_mfma_f32_16x16x32_bf16 v[150:153], v[248:251], v[232:235], v[150:153]
	v_mfma_f32_16x16x32_bf16 v[166:169], v[248:251], v[236:239], v[166:169]
	v_mfma_f32_16x16x32_bf16 v[182:185], v[248:251], v[240:243], v[182:185]
	s_waitcnt lgkmcnt(1)
	v_mfma_f32_16x16x32_bf16 v[138:141], v[252:255], v[228:231], v[138:141]
	v_mfma_f32_16x16x32_bf16 v[154:157], v[252:255], v[232:235], v[154:157]
	v_mfma_f32_16x16x32_bf16 v[170:173], v[252:255], v[236:239], v[170:173]
	v_mfma_f32_16x16x32_bf16 v[186:189], v[252:255], v[240:243], v[186:189]
	s_waitcnt lgkmcnt(0)
	v_mfma_f32_16x16x32_bf16 v[142:145], v[216:219], v[228:231], v[142:145]
	v_mfma_f32_16x16x32_bf16 v[158:161], v[216:219], v[232:235], v[158:161]
	v_mfma_f32_16x16x32_bf16 v[174:177], v[216:219], v[236:239], v[174:177]
	v_mfma_f32_16x16x32_bf16 v[190:193], v[216:219], v[240:243], v[190:193]
	s_sub_u32 s27, s27, 1
	s_cmp_lg_u32 s27, 0
	s_cbranch_scc1 .Lmg_loop
	s_barrier
	v_and_b32_e32 v213, 15, v196
	v_lshrrev_b32_e32 v214, 7, v196
	v_lshl_add_u32 v213, v214, 6, v213
	v_bfe_u32 v214, v196, 6, 1
	v_bfe_u32 v220, v196, 4, 2
	v_lshlrev_b32_e32 v220, 3, v220
	v_lshl_add_u32 v214, v214, 7, v220
	v_lshl_add_u32 v215, v213, 11, v214
	v_add_u32_e32 v220, 0x8000, v215
	v_add_u32_e32 v227, 0x10000, v215
	v_add_u32_e32 v0, 0x18000, v215
	s_add_u32 s38, s19, s2
	s_addc_u32 s39, s20, 0
	s_nop 0
	global_load_dwordx2 v[228:229], v215, s[38:39] offset:0
	global_load_dwordx2 v[230:231], v215, s[38:39] offset:32
	global_load_dwordx2 v[232:233], v215, s[38:39] offset:64
	global_load_dwordx2 v[234:235], v215, s[38:39] offset:96
	global_load_dwordx2 v[236:237], v220, s[38:39] offset:0
	global_load_dwordx2 v[238:239], v220, s[38:39] offset:32
	global_load_dwordx2 v[240:241], v220, s[38:39] offset:64
	global_load_dwordx2 v[242:243], v220, s[38:39] offset:96
	global_load_dwordx2 v[244:245], v227, s[38:39] offset:0
	global_load_dwordx2 v[246:247], v227, s[38:39] offset:32
	global_load_dwordx2 v[248:249], v227, s[38:39] offset:64
	global_load_dwordx2 v[250:251], v227, s[38:39] offset:96
	global_load_dwordx2 v[252:253], v0, s[38:39] offset:0
	global_load_dwordx2 v[254:255], v0, s[38:39] offset:32
	global_load_dwordx2 v[216:217], v0, s[38:39] offset:64
	global_load_dwordx2 v[218:219], v0, s[38:39] offset:96
	v_mul_f32_e32 v2, 0xbfb8aa3b, v2
	v_mul_f32_e32 v3, 0xbfb8aa3b, v3
	v_mul_f32_e32 v4, 0xbfb8aa3b, v4
	v_mul_f32_e32 v5, 0xbfb8aa3b, v5
	v_exp_f32_e32 v2, v2
	v_exp_f32_e32 v3, v3
	v_exp_f32_e32 v4, v4
	v_exp_f32_e32 v5, v5
	v_add_f32_e32 v2, 1.0, v2
	v_add_f32_e32 v3, 1.0, v3
	v_add_f32_e32 v4, 1.0, v4
	v_add_f32_e32 v5, 1.0, v5
	v_rcp_f32_e32 v2, v2
	v_rcp_f32_e32 v3, v3
	v_rcp_f32_e32 v4, v4
	v_rcp_f32_e32 v5, v5
	v_mul_f32_e32 v6, 0xbfb8aa3b, v6
	v_mul_f32_e32 v7, 0xbfb8aa3b, v7
	v_mul_f32_e32 v8, 0xbfb8aa3b, v8
	v_mul_f32_e32 v9, 0xbfb8aa3b, v9
	v_exp_f32_e32 v6, v6
	v_exp_f32_e32 v7, v7
	v_exp_f32_e32 v8, v8
	v_exp_f32_e32 v9, v9
	v_add_f32_e32 v6, 1.0, v6
	v_add_f32_e32 v7, 1.0, v7
	v_add_f32_e32 v8, 1.0, v8
	v_add_f32_e32 v9, 1.0, v9
	v_rcp_f32_e32 v6, v6
	v_rcp_f32_e32 v7, v7
	v_rcp_f32_e32 v8, v8
	v_rcp_f32_e32 v9, v9
	v_mul_f32_e32 v10, 0xbfb8aa3b, v10
	v_mul_f32_e32 v11, 0xbfb8aa3b, v11
	v_mul_f32_e32 v12, 0xbfb8aa3b, v12
	v_mul_f32_e32 v13, 0xbfb8aa3b, v13
	v_exp_f32_e32 v10, v10
	v_exp_f32_e32 v11, v11
	v_exp_f32_e32 v12, v12
	v_exp_f32_e32 v13, v13
	v_add_f32_e32 v10, 1.0, v10
	v_add_f32_e32 v11, 1.0, v11
	v_add_f32_e32 v12, 1.0, v12
	v_add_f32_e32 v13, 1.0, v13
	v_rcp_f32_e32 v10, v10
	v_rcp_f32_e32 v11, v11
	v_rcp_f32_e32 v12, v12
	v_rcp_f32_e32 v13, v13
	v_mul_f32_e32 v14, 0xbfb8aa3b, v14
	v_mul_f32_e32 v15, 0xbfb8aa3b, v15
	v_mul_f32_e32 v16, 0xbfb8aa3b, v16
	v_mul_f32_e32 v17, 0xbfb8aa3b, v17
	v_exp_f32_e32 v14, v14
	v_exp_f32_e32 v15, v15
	v_exp_f32_e32 v16, v16
	v_exp_f32_e32 v17, v17
	v_add_f32_e32 v14, 1.0, v14
	v_add_f32_e32 v15, 1.0, v15
	v_add_f32_e32 v16, 1.0, v16
	v_add_f32_e32 v17, 1.0, v17
	v_rcp_f32_e32 v14, v14
	v_rcp_f32_e32 v15, v15
	v_rcp_f32_e32 v16, v16
	v_rcp_f32_e32 v17, v17
	v_mul_f32_e32 v18, 0xbfb8aa3b, v18
	v_mul_f32_e32 v19, 0xbfb8aa3b, v19
	v_mul_f32_e32 v20, 0xbfb8aa3b, v20
	v_mul_f32_e32 v21, 0xbfb8aa3b, v21
	v_exp_f32_e32 v18, v18
	v_exp_f32_e32 v19, v19
	v_exp_f32_e32 v20, v20
	v_exp_f32_e32 v21, v21
	v_add_f32_e32 v18, 1.0, v18
	v_add_f32_e32 v19, 1.0, v19
	v_add_f32_e32 v20, 1.0, v20
	v_add_f32_e32 v21, 1.0, v21
	v_rcp_f32_e32 v18, v18
	v_rcp_f32_e32 v19, v19
	v_rcp_f32_e32 v20, v20
	v_rcp_f32_e32 v21, v21
	v_mul_f32_e32 v22, 0xbfb8aa3b, v22
	v_mul_f32_e32 v23, 0xbfb8aa3b, v23
	v_mul_f32_e32 v24, 0xbfb8aa3b, v24
	v_mul_f32_e32 v25, 0xbfb8aa3b, v25
	v_exp_f32_e32 v22, v22
	v_exp_f32_e32 v23, v23
	v_exp_f32_e32 v24, v24
	v_exp_f32_e32 v25, v25
	v_add_f32_e32 v22, 1.0, v22
	v_add_f32_e32 v23, 1.0, v23
	v_add_f32_e32 v24, 1.0, v24
	v_add_f32_e32 v25, 1.0, v25
	v_rcp_f32_e32 v22, v22
	v_rcp_f32_e32 v23, v23
	v_rcp_f32_e32 v24, v24
	v_rcp_f32_e32 v25, v25
	v_mul_f32_e32 v26, 0xbfb8aa3b, v26
	v_mul_f32_e32 v27, 0xbfb8aa3b, v27
	v_mul_f32_e32 v28, 0xbfb8aa3b, v28
	v_mul_f32_e32 v29, 0xbfb8aa3b, v29
	v_exp_f32_e32 v26, v26
	v_exp_f32_e32 v27, v27
	v_exp_f32_e32 v28, v28
	v_exp_f32_e32 v29, v29
	v_add_f32_e32 v26, 1.0, v26
	v_add_f32_e32 v27, 1.0, v27
	v_add_f32_e32 v28, 1.0, v28
	v_add_f32_e32 v29, 1.0, v29
	v_rcp_f32_e32 v26, v26
	v_rcp_f32_e32 v27, v27
	v_rcp_f32_e32 v28, v28
	v_rcp_f32_e32 v29, v29
	v_mul_f32_e32 v30, 0xbfb8aa3b, v30
	v_mul_f32_e32 v31, 0xbfb8aa3b, v31
	v_mul_f32_e32 v32, 0xbfb8aa3b, v32
	v_mul_f32_e32 v33, 0xbfb8aa3b, v33
	v_exp_f32_e32 v30, v30
	v_exp_f32_e32 v31, v31
	v_exp_f32_e32 v32, v32
	v_exp_f32_e32 v33, v33
	v_add_f32_e32 v30, 1.0, v30
	v_add_f32_e32 v31, 1.0, v31
	v_add_f32_e32 v32, 1.0, v32
	v_add_f32_e32 v33, 1.0, v33
	v_rcp_f32_e32 v30, v30
	v_rcp_f32_e32 v31, v31
	v_rcp_f32_e32 v32, v32
	v_rcp_f32_e32 v33, v33
	v_mul_f32_e32 v34, 0xbfb8aa3b, v34
	v_mul_f32_e32 v35, 0xbfb8aa3b, v35
	v_mul_f32_e32 v36, 0xbfb8aa3b, v36
	v_mul_f32_e32 v37, 0xbfb8aa3b, v37
	v_exp_f32_e32 v34, v34
	v_exp_f32_e32 v35, v35
	v_exp_f32_e32 v36, v36
	v_exp_f32_e32 v37, v37
	v_add_f32_e32 v34, 1.0, v34
	v_add_f32_e32 v35, 1.0, v35
	v_add_f32_e32 v36, 1.0, v36
	v_add_f32_e32 v37, 1.0, v37
	v_rcp_f32_e32 v34, v34
	v_rcp_f32_e32 v35, v35
	v_rcp_f32_e32 v36, v36
	v_rcp_f32_e32 v37, v37
	v_mul_f32_e32 v38, 0xbfb8aa3b, v38
	v_mul_f32_e32 v39, 0xbfb8aa3b, v39
	v_mul_f32_e32 v40, 0xbfb8aa3b, v40
	v_mul_f32_e32 v41, 0xbfb8aa3b, v41
	v_exp_f32_e32 v38, v38
	v_exp_f32_e32 v39, v39
	v_exp_f32_e32 v40, v40
	v_exp_f32_e32 v41, v41
	v_add_f32_e32 v38, 1.0, v38
	v_add_f32_e32 v39, 1.0, v39
	v_add_f32_e32 v40, 1.0, v40
	v_add_f32_e32 v41, 1.0, v41
	v_rcp_f32_e32 v38, v38
	v_rcp_f32_e32 v39, v39
	v_rcp_f32_e32 v40, v40
	v_rcp_f32_e32 v41, v41
	v_mul_f32_e32 v42, 0xbfb8aa3b, v42
	v_mul_f32_e32 v43, 0xbfb8aa3b, v43
	v_mul_f32_e32 v44, 0xbfb8aa3b, v44
	v_mul_f32_e32 v45, 0xbfb8aa3b, v45
	v_exp_f32_e32 v42, v42
	v_exp_f32_e32 v43, v43
	v_exp_f32_e32 v44, v44
	v_exp_f32_e32 v45, v45
	v_add_f32_e32 v42, 1.0, v42
	v_add_f32_e32 v43, 1.0, v43
	v_add_f32_e32 v44, 1.0, v44
	v_add_f32_e32 v45, 1.0, v45
	v_rcp_f32_e32 v42, v42
	v_rcp_f32_e32 v43, v43
	v_rcp_f32_e32 v44, v44
	v_rcp_f32_e32 v45, v45
	v_mul_f32_e32 v46, 0xbfb8aa3b, v46
	v_mul_f32_e32 v47, 0xbfb8aa3b, v47
	v_mul_f32_e32 v48, 0xbfb8aa3b, v48
	v_mul_f32_e32 v49, 0xbfb8aa3b, v49
	v_exp_f32_e32 v46, v46
	v_exp_f32_e32 v47, v47
	v_exp_f32_e32 v48, v48
	v_exp_f32_e32 v49, v49
	v_add_f32_e32 v46, 1.0, v46
	v_add_f32_e32 v47, 1.0, v47
	v_add_f32_e32 v48, 1.0, v48
	v_add_f32_e32 v49, 1.0, v49
	v_rcp_f32_e32 v46, v46
	v_rcp_f32_e32 v47, v47
	v_rcp_f32_e32 v48, v48
	v_rcp_f32_e32 v49, v49
	v_mul_f32_e32 v50, 0xbfb8aa3b, v50
	v_mul_f32_e32 v51, 0xbfb8aa3b, v51
	v_mul_f32_e32 v52, 0xbfb8aa3b, v52
	v_mul_f32_e32 v53, 0xbfb8aa3b, v53
	v_exp_f32_e32 v50, v50
	v_exp_f32_e32 v51, v51
	v_exp_f32_e32 v52, v52
	v_exp_f32_e32 v53, v53
	v_add_f32_e32 v50, 1.0, v50
	v_add_f32_e32 v51, 1.0, v51
	v_add_f32_e32 v52, 1.0, v52
	v_add_f32_e32 v53, 1.0, v53
	v_rcp_f32_e32 v50, v50
	v_rcp_f32_e32 v51, v51
	v_rcp_f32_e32 v52, v52
	v_rcp_f32_e32 v53, v53
	v_mul_f32_e32 v54, 0xbfb8aa3b, v54
	v_mul_f32_e32 v55, 0xbfb8aa3b, v55
	v_mul_f32_e32 v56, 0xbfb8aa3b, v56
	v_mul_f32_e32 v57, 0xbfb8aa3b, v57
	v_exp_f32_e32 v54, v54
	v_exp_f32_e32 v55, v55
	v_exp_f32_e32 v56, v56
	v_exp_f32_e32 v57, v57
	v_add_f32_e32 v54, 1.0, v54
	v_add_f32_e32 v55, 1.0, v55
	v_add_f32_e32 v56, 1.0, v56
	v_add_f32_e32 v57, 1.0, v57
	v_rcp_f32_e32 v54, v54
	v_rcp_f32_e32 v55, v55
	v_rcp_f32_e32 v56, v56
	v_rcp_f32_e32 v57, v57
	v_mul_f32_e32 v58, 0xbfb8aa3b, v58
	v_mul_f32_e32 v59, 0xbfb8aa3b, v59
	v_mul_f32_e32 v60, 0xbfb8aa3b, v60
	v_mul_f32_e32 v61, 0xbfb8aa3b, v61
	v_exp_f32_e32 v58, v58
	v_exp_f32_e32 v59, v59
	v_exp_f32_e32 v60, v60
	v_exp_f32_e32 v61, v61
	v_add_f32_e32 v58, 1.0, v58
	v_add_f32_e32 v59, 1.0, v59
	v_add_f32_e32 v60, 1.0, v60
	v_add_f32_e32 v61, 1.0, v61
	v_rcp_f32_e32 v58, v58
	v_rcp_f32_e32 v59, v59
	v_rcp_f32_e32 v60, v60
	v_rcp_f32_e32 v61, v61
	v_mul_f32_e32 v62, 0xbfb8aa3b, v62
	v_mul_f32_e32 v63, 0xbfb8aa3b, v63
	v_mul_f32_e32 v64, 0xbfb8aa3b, v64
	v_mul_f32_e32 v65, 0xbfb8aa3b, v65
	v_exp_f32_e32 v62, v62
	v_exp_f32_e32 v63, v63
	v_exp_f32_e32 v64, v64
	v_exp_f32_e32 v65, v65
	v_add_f32_e32 v62, 1.0, v62
	v_add_f32_e32 v63, 1.0, v63
	v_add_f32_e32 v64, 1.0, v64
	v_add_f32_e32 v65, 1.0, v65
	v_rcp_f32_e32 v62, v62
	v_rcp_f32_e32 v63, v63
	v_rcp_f32_e32 v64, v64
	v_rcp_f32_e32 v65, v65
	s_waitcnt vmcnt(0)
	v_lshlrev_b32_e32 v194, 16, v228
	v_and_b32_e32 v195, 0xffff0000, v228
	v_lshlrev_b32_e32 v213, 16, v229
	v_and_b32_e32 v214, 0xffff0000, v229
	v_fma_f32 v2, v194, v2, v1
	v_fma_f32 v3, v195, v3, v1
	v_fma_f32 v4, v213, v4, v1
	v_fma_f32 v5, v214, v5, v1
	v_lshlrev_b32_e32 v194, 16, v230
	v_and_b32_e32 v195, 0xffff0000, v230
	v_lshlrev_b32_e32 v213, 16, v231
	v_and_b32_e32 v214, 0xffff0000, v231
	v_fma_f32 v6, v194, v6, v1
	v_fma_f32 v7, v195, v7, v1
	v_fma_f32 v8, v213, v8, v1
	v_fma_f32 v9, v214, v9, v1
	v_lshlrev_b32_e32 v194, 16, v232
	v_and_b32_e32 v195, 0xffff0000, v232
	v_lshlrev_b32_e32 v213, 16, v233
	v_and_b32_e32 v214, 0xffff0000, v233
	v_fma_f32 v10, v194, v10, v1
	v_fma_f32 v11, v195, v11, v1
	v_fma_f32 v12, v213, v12, v1
	v_fma_f32 v13, v214, v13, v1
	v_lshlrev_b32_e32 v194, 16, v234
	v_and_b32_e32 v195, 0xffff0000, v234
	v_lshlrev_b32_e32 v213, 16, v235
	v_and_b32_e32 v214, 0xffff0000, v235
	v_fma_f32 v14, v194, v14, v1
	v_fma_f32 v15, v195, v15, v1
	v_fma_f32 v16, v213, v16, v1
	v_fma_f32 v17, v214, v17, v1
	v_lshlrev_b32_e32 v194, 16, v236
	v_and_b32_e32 v195, 0xffff0000, v236
	v_lshlrev_b32_e32 v213, 16, v237
	v_and_b32_e32 v214, 0xffff0000, v237
	v_fma_f32 v18, v194, v18, v1
	v_fma_f32 v19, v195, v19, v1
	v_fma_f32 v20, v213, v20, v1
	v_fma_f32 v21, v214, v21, v1
	v_lshlrev_b32_e32 v194, 16, v238
	v_and_b32_e32 v195, 0xffff0000, v238
	v_lshlrev_b32_e32 v213, 16, v239
	v_and_b32_e32 v214, 0xffff0000, v239
	v_fma_f32 v22, v194, v22, v1
	v_fma_f32 v23, v195, v23, v1
	v_fma_f32 v24, v213, v24, v1
	v_fma_f32 v25, v214, v25, v1
	v_lshlrev_b32_e32 v194, 16, v240
	v_and_b32_e32 v195, 0xffff0000, v240
	v_lshlrev_b32_e32 v213, 16, v241
	v_and_b32_e32 v214, 0xffff0000, v241
	v_fma_f32 v26, v194, v26, v1
	v_fma_f32 v27, v195, v27, v1
	v_fma_f32 v28, v213, v28, v1
	v_fma_f32 v29, v214, v29, v1
	v_lshlrev_b32_e32 v194, 16, v242
	v_and_b32_e32 v195, 0xffff0000, v242
	v_lshlrev_b32_e32 v213, 16, v243
	v_and_b32_e32 v214, 0xffff0000, v243
	v_fma_f32 v30, v194, v30, v1
	v_fma_f32 v31, v195, v31, v1
	v_fma_f32 v32, v213, v32, v1
	v_fma_f32 v33, v214, v33, v1
	v_lshlrev_b32_e32 v194, 16, v244
	v_and_b32_e32 v195, 0xffff0000, v244
	v_lshlrev_b32_e32 v213, 16, v245
	v_and_b32_e32 v214, 0xffff0000, v245
	v_fma_f32 v34, v194, v34, v1
	v_fma_f32 v35, v195, v35, v1
	v_fma_f32 v36, v213, v36, v1
	v_fma_f32 v37, v214, v37, v1
	v_lshlrev_b32_e32 v194, 16, v246
	v_and_b32_e32 v195, 0xffff0000, v246
	v_lshlrev_b32_e32 v213, 16, v247
	v_and_b32_e32 v214, 0xffff0000, v247
	v_fma_f32 v38, v194, v38, v1
	v_fma_f32 v39, v195, v39, v1
	v_fma_f32 v40, v213, v40, v1
	v_fma_f32 v41, v214, v41, v1
	v_lshlrev_b32_e32 v194, 16, v248
	v_and_b32_e32 v195, 0xffff0000, v248
	v_lshlrev_b32_e32 v213, 16, v249
	v_and_b32_e32 v214, 0xffff0000, v249
	v_fma_f32 v42, v194, v42, v1
	v_fma_f32 v43, v195, v43, v1
	v_fma_f32 v44, v213, v44, v1
	v_fma_f32 v45, v214, v45, v1
	v_lshlrev_b32_e32 v194, 16, v250
	v_and_b32_e32 v195, 0xffff0000, v250
	v_lshlrev_b32_e32 v213, 16, v251
	v_and_b32_e32 v214, 0xffff0000, v251
	v_fma_f32 v46, v194, v46, v1
	v_fma_f32 v47, v195, v47, v1
	v_fma_f32 v48, v213, v48, v1
	v_fma_f32 v49, v214, v49, v1
	v_lshlrev_b32_e32 v194, 16, v252
	v_and_b32_e32 v195, 0xffff0000, v252
	v_lshlrev_b32_e32 v213, 16, v253
	v_and_b32_e32 v214, 0xffff0000, v253
	v_fma_f32 v50, v194, v50, v1
	v_fma_f32 v51, v195, v51, v1
	v_fma_f32 v52, v213, v52, v1
	v_fma_f32 v53, v214, v53, v1
	v_lshlrev_b32_e32 v194, 16, v254
	v_and_b32_e32 v195, 0xffff0000, v254
	v_lshlrev_b32_e32 v213, 16, v255
	v_and_b32_e32 v214, 0xffff0000, v255
	v_fma_f32 v54, v194, v54, v1
	v_fma_f32 v55, v195, v55, v1
	v_fma_f32 v56, v213, v56, v1
	v_fma_f32 v57, v214, v57, v1
	v_lshlrev_b32_e32 v194, 16, v216
	v_and_b32_e32 v195, 0xffff0000, v216
	v_lshlrev_b32_e32 v213, 16, v217
	v_and_b32_e32 v214, 0xffff0000, v217
	v_fma_f32 v58, v194, v58, v1
	v_fma_f32 v59, v195, v59, v1
	v_fma_f32 v60, v213, v60, v1
	v_fma_f32 v61, v214, v61, v1
	v_lshlrev_b32_e32 v194, 16, v218
	v_and_b32_e32 v195, 0xffff0000, v218
	v_lshlrev_b32_e32 v213, 16, v219
	v_and_b32_e32 v214, 0xffff0000, v219
	v_fma_f32 v62, v194, v62, v1
	v_fma_f32 v63, v195, v63, v1
	v_fma_f32 v64, v213, v64, v1
	v_fma_f32 v65, v214, v65, v1
	s_add_u32 s38, s42, 0x1241c000
	s_addc_u32 s39, s43, 0
	s_add_u32 s38, s38, s2
	s_addc_u32 s39, s39, 0
	s_nop 0
	global_load_dwordx2 v[228:229], v215, s[38:39] offset:0
	global_load_dwordx2 v[230:231], v215, s[38:39] offset:32
	global_load_dwordx2 v[232:233], v215, s[38:39] offset:64
	global_load_dwordx2 v[234:235], v215, s[38:39] offset:96
	global_load_dwordx2 v[236:237], v220, s[38:39] offset:0
	global_load_dwordx2 v[238:239], v220, s[38:39] offset:32
	global_load_dwordx2 v[240:241], v220, s[38:39] offset:64
	global_load_dwordx2 v[242:243], v220, s[38:39] offset:96
	global_load_dwordx2 v[244:245], v227, s[38:39] offset:0
	global_load_dwordx2 v[246:247], v227, s[38:39] offset:32
	global_load_dwordx2 v[248:249], v227, s[38:39] offset:64
	global_load_dwordx2 v[250:251], v227, s[38:39] offset:96
	global_load_dwordx2 v[252:253], v0, s[38:39] offset:0
	global_load_dwordx2 v[254:255], v0, s[38:39] offset:32
	global_load_dwordx2 v[216:217], v0, s[38:39] offset:64
	global_load_dwordx2 v[218:219], v0, s[38:39] offset:96
	v_mul_f32_e32 v66, 0xbfb8aa3b, v66
	v_mul_f32_e32 v67, 0xbfb8aa3b, v67
	v_mul_f32_e32 v68, 0xbfb8aa3b, v68
	v_mul_f32_e32 v69, 0xbfb8aa3b, v69
	v_exp_f32_e32 v66, v66
	v_exp_f32_e32 v67, v67
	v_exp_f32_e32 v68, v68
	v_exp_f32_e32 v69, v69
	v_add_f32_e32 v66, 1.0, v66
	v_add_f32_e32 v67, 1.0, v67
	v_add_f32_e32 v68, 1.0, v68
	v_add_f32_e32 v69, 1.0, v69
	v_rcp_f32_e32 v66, v66
	v_rcp_f32_e32 v67, v67
	v_rcp_f32_e32 v68, v68
	v_rcp_f32_e32 v69, v69
	v_mul_f32_e32 v70, 0xbfb8aa3b, v70
	v_mul_f32_e32 v71, 0xbfb8aa3b, v71
	v_mul_f32_e32 v72, 0xbfb8aa3b, v72
	v_mul_f32_e32 v73, 0xbfb8aa3b, v73
	v_exp_f32_e32 v70, v70
	v_exp_f32_e32 v71, v71
	v_exp_f32_e32 v72, v72
	v_exp_f32_e32 v73, v73
	v_add_f32_e32 v70, 1.0, v70
	v_add_f32_e32 v71, 1.0, v71
	v_add_f32_e32 v72, 1.0, v72
	v_add_f32_e32 v73, 1.0, v73
	v_rcp_f32_e32 v70, v70
	v_rcp_f32_e32 v71, v71
	v_rcp_f32_e32 v72, v72
	v_rcp_f32_e32 v73, v73
	v_mul_f32_e32 v74, 0xbfb8aa3b, v74
	v_mul_f32_e32 v75, 0xbfb8aa3b, v75
	v_mul_f32_e32 v76, 0xbfb8aa3b, v76
	v_mul_f32_e32 v77, 0xbfb8aa3b, v77
	v_exp_f32_e32 v74, v74
	v_exp_f32_e32 v75, v75
	v_exp_f32_e32 v76, v76
	v_exp_f32_e32 v77, v77
	v_add_f32_e32 v74, 1.0, v74
	v_add_f32_e32 v75, 1.0, v75
	v_add_f32_e32 v76, 1.0, v76
	v_add_f32_e32 v77, 1.0, v77
	v_rcp_f32_e32 v74, v74
	v_rcp_f32_e32 v75, v75
	v_rcp_f32_e32 v76, v76
	v_rcp_f32_e32 v77, v77
	v_mul_f32_e32 v78, 0xbfb8aa3b, v78
	v_mul_f32_e32 v79, 0xbfb8aa3b, v79
	v_mul_f32_e32 v80, 0xbfb8aa3b, v80
	v_mul_f32_e32 v81, 0xbfb8aa3b, v81
	v_exp_f32_e32 v78, v78
	v_exp_f32_e32 v79, v79
	v_exp_f32_e32 v80, v80
	v_exp_f32_e32 v81, v81
	v_add_f32_e32 v78, 1.0, v78
	v_add_f32_e32 v79, 1.0, v79
	v_add_f32_e32 v80, 1.0, v80
	v_add_f32_e32 v81, 1.0, v81
	v_rcp_f32_e32 v78, v78
	v_rcp_f32_e32 v79, v79
	v_rcp_f32_e32 v80, v80
	v_rcp_f32_e32 v81, v81
	v_mul_f32_e32 v82, 0xbfb8aa3b, v82
	v_mul_f32_e32 v83, 0xbfb8aa3b, v83
	v_mul_f32_e32 v84, 0xbfb8aa3b, v84
	v_mul_f32_e32 v85, 0xbfb8aa3b, v85
	v_exp_f32_e32 v82, v82
	v_exp_f32_e32 v83, v83
	v_exp_f32_e32 v84, v84
	v_exp_f32_e32 v85, v85
	v_add_f32_e32 v82, 1.0, v82
	v_add_f32_e32 v83, 1.0, v83
	v_add_f32_e32 v84, 1.0, v84
	v_add_f32_e32 v85, 1.0, v85
	v_rcp_f32_e32 v82, v82
	v_rcp_f32_e32 v83, v83
	v_rcp_f32_e32 v84, v84
	v_rcp_f32_e32 v85, v85
	v_mul_f32_e32 v86, 0xbfb8aa3b, v86
	v_mul_f32_e32 v87, 0xbfb8aa3b, v87
	v_mul_f32_e32 v88, 0xbfb8aa3b, v88
	v_mul_f32_e32 v89, 0xbfb8aa3b, v89
	v_exp_f32_e32 v86, v86
	v_exp_f32_e32 v87, v87
	v_exp_f32_e32 v88, v88
	v_exp_f32_e32 v89, v89
	v_add_f32_e32 v86, 1.0, v86
	v_add_f32_e32 v87, 1.0, v87
	v_add_f32_e32 v88, 1.0, v88
	v_add_f32_e32 v89, 1.0, v89
	v_rcp_f32_e32 v86, v86
	v_rcp_f32_e32 v87, v87
	v_rcp_f32_e32 v88, v88
	v_rcp_f32_e32 v89, v89
	v_mul_f32_e32 v90, 0xbfb8aa3b, v90
	v_mul_f32_e32 v91, 0xbfb8aa3b, v91
	v_mul_f32_e32 v92, 0xbfb8aa3b, v92
	v_mul_f32_e32 v93, 0xbfb8aa3b, v93
	v_exp_f32_e32 v90, v90
	v_exp_f32_e32 v91, v91
	v_exp_f32_e32 v92, v92
	v_exp_f32_e32 v93, v93
	v_add_f32_e32 v90, 1.0, v90
	v_add_f32_e32 v91, 1.0, v91
	v_add_f32_e32 v92, 1.0, v92
	v_add_f32_e32 v93, 1.0, v93
	v_rcp_f32_e32 v90, v90
	v_rcp_f32_e32 v91, v91
	v_rcp_f32_e32 v92, v92
	v_rcp_f32_e32 v93, v93
	v_mul_f32_e32 v94, 0xbfb8aa3b, v94
	v_mul_f32_e32 v95, 0xbfb8aa3b, v95
	v_mul_f32_e32 v96, 0xbfb8aa3b, v96
	v_mul_f32_e32 v97, 0xbfb8aa3b, v97
	v_exp_f32_e32 v94, v94
	v_exp_f32_e32 v95, v95
	v_exp_f32_e32 v96, v96
	v_exp_f32_e32 v97, v97
	v_add_f32_e32 v94, 1.0, v94
	v_add_f32_e32 v95, 1.0, v95
	v_add_f32_e32 v96, 1.0, v96
	v_add_f32_e32 v97, 1.0, v97
	v_rcp_f32_e32 v94, v94
	v_rcp_f32_e32 v95, v95
	v_rcp_f32_e32 v96, v96
	v_rcp_f32_e32 v97, v97
	v_mul_f32_e32 v98, 0xbfb8aa3b, v98
	v_mul_f32_e32 v99, 0xbfb8aa3b, v99
	v_mul_f32_e32 v100, 0xbfb8aa3b, v100
	v_mul_f32_e32 v101, 0xbfb8aa3b, v101
	v_exp_f32_e32 v98, v98
	v_exp_f32_e32 v99, v99
	v_exp_f32_e32 v100, v100
	v_exp_f32_e32 v101, v101
	v_add_f32_e32 v98, 1.0, v98
	v_add_f32_e32 v99, 1.0, v99
	v_add_f32_e32 v100, 1.0, v100
	v_add_f32_e32 v101, 1.0, v101
	v_rcp_f32_e32 v98, v98
	v_rcp_f32_e32 v99, v99
	v_rcp_f32_e32 v100, v100
	v_rcp_f32_e32 v101, v101
	v_mul_f32_e32 v102, 0xbfb8aa3b, v102
	v_mul_f32_e32 v103, 0xbfb8aa3b, v103
	v_mul_f32_e32 v104, 0xbfb8aa3b, v104
	v_mul_f32_e32 v105, 0xbfb8aa3b, v105
	v_exp_f32_e32 v102, v102
	v_exp_f32_e32 v103, v103
	v_exp_f32_e32 v104, v104
	v_exp_f32_e32 v105, v105
	v_add_f32_e32 v102, 1.0, v102
	v_add_f32_e32 v103, 1.0, v103
	v_add_f32_e32 v104, 1.0, v104
	v_add_f32_e32 v105, 1.0, v105
	v_rcp_f32_e32 v102, v102
	v_rcp_f32_e32 v103, v103
	v_rcp_f32_e32 v104, v104
	v_rcp_f32_e32 v105, v105
	v_mul_f32_e32 v106, 0xbfb8aa3b, v106
	v_mul_f32_e32 v107, 0xbfb8aa3b, v107
	v_mul_f32_e32 v108, 0xbfb8aa3b, v108
	v_mul_f32_e32 v109, 0xbfb8aa3b, v109
	v_exp_f32_e32 v106, v106
	v_exp_f32_e32 v107, v107
	v_exp_f32_e32 v108, v108
	v_exp_f32_e32 v109, v109
	v_add_f32_e32 v106, 1.0, v106
	v_add_f32_e32 v107, 1.0, v107
	v_add_f32_e32 v108, 1.0, v108
	v_add_f32_e32 v109, 1.0, v109
	v_rcp_f32_e32 v106, v106
	v_rcp_f32_e32 v107, v107
	v_rcp_f32_e32 v108, v108
	v_rcp_f32_e32 v109, v109
	v_mul_f32_e32 v110, 0xbfb8aa3b, v110
	v_mul_f32_e32 v111, 0xbfb8aa3b, v111
	v_mul_f32_e32 v112, 0xbfb8aa3b, v112
	v_mul_f32_e32 v113, 0xbfb8aa3b, v113
	v_exp_f32_e32 v110, v110
	v_exp_f32_e32 v111, v111
	v_exp_f32_e32 v112, v112
	v_exp_f32_e32 v113, v113
	v_add_f32_e32 v110, 1.0, v110
	v_add_f32_e32 v111, 1.0, v111
	v_add_f32_e32 v112, 1.0, v112
	v_add_f32_e32 v113, 1.0, v113
	v_rcp_f32_e32 v110, v110
	v_rcp_f32_e32 v111, v111
	v_rcp_f32_e32 v112, v112
	v_rcp_f32_e32 v113, v113
	v_mul_f32_e32 v114, 0xbfb8aa3b, v114
	v_mul_f32_e32 v115, 0xbfb8aa3b, v115
	v_mul_f32_e32 v116, 0xbfb8aa3b, v116
	v_mul_f32_e32 v117, 0xbfb8aa3b, v117
	v_exp_f32_e32 v114, v114
	v_exp_f32_e32 v115, v115
	v_exp_f32_e32 v116, v116
	v_exp_f32_e32 v117, v117
	v_add_f32_e32 v114, 1.0, v114
	v_add_f32_e32 v115, 1.0, v115
	v_add_f32_e32 v116, 1.0, v116
	v_add_f32_e32 v117, 1.0, v117
	v_rcp_f32_e32 v114, v114
	v_rcp_f32_e32 v115, v115
	v_rcp_f32_e32 v116, v116
	v_rcp_f32_e32 v117, v117
	v_mul_f32_e32 v118, 0xbfb8aa3b, v118
	v_mul_f32_e32 v119, 0xbfb8aa3b, v119
	v_mul_f32_e32 v120, 0xbfb8aa3b, v120
	v_mul_f32_e32 v121, 0xbfb8aa3b, v121
	v_exp_f32_e32 v118, v118
	v_exp_f32_e32 v119, v119
	v_exp_f32_e32 v120, v120
	v_exp_f32_e32 v121, v121
	v_add_f32_e32 v118, 1.0, v118
	v_add_f32_e32 v119, 1.0, v119
	v_add_f32_e32 v120, 1.0, v120
	v_add_f32_e32 v121, 1.0, v121
	v_rcp_f32_e32 v118, v118
	v_rcp_f32_e32 v119, v119
	v_rcp_f32_e32 v120, v120
	v_rcp_f32_e32 v121, v121
	v_mul_f32_e32 v122, 0xbfb8aa3b, v122
	v_mul_f32_e32 v123, 0xbfb8aa3b, v123
	v_mul_f32_e32 v124, 0xbfb8aa3b, v124
	v_mul_f32_e32 v125, 0xbfb8aa3b, v125
	v_exp_f32_e32 v122, v122
	v_exp_f32_e32 v123, v123
	v_exp_f32_e32 v124, v124
	v_exp_f32_e32 v125, v125
	v_add_f32_e32 v122, 1.0, v122
	v_add_f32_e32 v123, 1.0, v123
	v_add_f32_e32 v124, 1.0, v124
	v_add_f32_e32 v125, 1.0, v125
	v_rcp_f32_e32 v122, v122
	v_rcp_f32_e32 v123, v123
	v_rcp_f32_e32 v124, v124
	v_rcp_f32_e32 v125, v125
	v_mul_f32_e32 v126, 0xbfb8aa3b, v126
	v_mul_f32_e32 v127, 0xbfb8aa3b, v127
	v_mul_f32_e32 v128, 0xbfb8aa3b, v128
	v_mul_f32_e32 v129, 0xbfb8aa3b, v129
	v_exp_f32_e32 v126, v126
	v_exp_f32_e32 v127, v127
	v_exp_f32_e32 v128, v128
	v_exp_f32_e32 v129, v129
	v_add_f32_e32 v126, 1.0, v126
	v_add_f32_e32 v127, 1.0, v127
	v_add_f32_e32 v128, 1.0, v128
	v_add_f32_e32 v129, 1.0, v129
	v_rcp_f32_e32 v126, v126
	v_rcp_f32_e32 v127, v127
	v_rcp_f32_e32 v128, v128
	v_rcp_f32_e32 v129, v129
	s_waitcnt vmcnt(0)
	v_lshlrev_b32_e32 v194, 16, v228
	v_and_b32_e32 v195, 0xffff0000, v228
	v_lshlrev_b32_e32 v213, 16, v229
	v_and_b32_e32 v214, 0xffff0000, v229
	v_fma_f32 v2, v194, v66, v2
	v_fma_f32 v3, v195, v67, v3
	v_fma_f32 v4, v213, v68, v4
	v_fma_f32 v5, v214, v69, v5
	v_lshlrev_b32_e32 v194, 16, v230
	v_and_b32_e32 v195, 0xffff0000, v230
	v_lshlrev_b32_e32 v213, 16, v231
	v_and_b32_e32 v214, 0xffff0000, v231
	v_fma_f32 v6, v194, v70, v6
	v_fma_f32 v7, v195, v71, v7
	v_fma_f32 v8, v213, v72, v8
	v_fma_f32 v9, v214, v73, v9
	v_lshlrev_b32_e32 v194, 16, v232
	v_and_b32_e32 v195, 0xffff0000, v232
	v_lshlrev_b32_e32 v213, 16, v233
	v_and_b32_e32 v214, 0xffff0000, v233
	v_fma_f32 v10, v194, v74, v10
	v_fma_f32 v11, v195, v75, v11
	v_fma_f32 v12, v213, v76, v12
	v_fma_f32 v13, v214, v77, v13
	v_lshlrev_b32_e32 v194, 16, v234
	v_and_b32_e32 v195, 0xffff0000, v234
	v_lshlrev_b32_e32 v213, 16, v235
	v_and_b32_e32 v214, 0xffff0000, v235
	v_fma_f32 v14, v194, v78, v14
	v_fma_f32 v15, v195, v79, v15
	v_fma_f32 v16, v213, v80, v16
	v_fma_f32 v17, v214, v81, v17
	v_lshlrev_b32_e32 v194, 16, v236
	v_and_b32_e32 v195, 0xffff0000, v236
	v_lshlrev_b32_e32 v213, 16, v237
	v_and_b32_e32 v214, 0xffff0000, v237
	v_fma_f32 v18, v194, v82, v18
	v_fma_f32 v19, v195, v83, v19
	v_fma_f32 v20, v213, v84, v20
	v_fma_f32 v21, v214, v85, v21
	v_lshlrev_b32_e32 v194, 16, v238
	v_and_b32_e32 v195, 0xffff0000, v238
	v_lshlrev_b32_e32 v213, 16, v239
	v_and_b32_e32 v214, 0xffff0000, v239
	v_fma_f32 v22, v194, v86, v22
	v_fma_f32 v23, v195, v87, v23
	v_fma_f32 v24, v213, v88, v24
	v_fma_f32 v25, v214, v89, v25
	v_lshlrev_b32_e32 v194, 16, v240
	v_and_b32_e32 v195, 0xffff0000, v240
	v_lshlrev_b32_e32 v213, 16, v241
	v_and_b32_e32 v214, 0xffff0000, v241
	v_fma_f32 v26, v194, v90, v26
	v_fma_f32 v27, v195, v91, v27
	v_fma_f32 v28, v213, v92, v28
	v_fma_f32 v29, v214, v93, v29
	v_lshlrev_b32_e32 v194, 16, v242
	v_and_b32_e32 v195, 0xffff0000, v242
	v_lshlrev_b32_e32 v213, 16, v243
	v_and_b32_e32 v214, 0xffff0000, v243
	v_fma_f32 v30, v194, v94, v30
	v_fma_f32 v31, v195, v95, v31
	v_fma_f32 v32, v213, v96, v32
	v_fma_f32 v33, v214, v97, v33
	v_lshlrev_b32_e32 v194, 16, v244
	v_and_b32_e32 v195, 0xffff0000, v244
	v_lshlrev_b32_e32 v213, 16, v245
	v_and_b32_e32 v214, 0xffff0000, v245
	v_fma_f32 v34, v194, v98, v34
	v_fma_f32 v35, v195, v99, v35
	v_fma_f32 v36, v213, v100, v36
	v_fma_f32 v37, v214, v101, v37
	v_lshlrev_b32_e32 v194, 16, v246
	v_and_b32_e32 v195, 0xffff0000, v246
	v_lshlrev_b32_e32 v213, 16, v247
	v_and_b32_e32 v214, 0xffff0000, v247
	v_fma_f32 v38, v194, v102, v38
	v_fma_f32 v39, v195, v103, v39
	v_fma_f32 v40, v213, v104, v40
	v_fma_f32 v41, v214, v105, v41
	v_lshlrev_b32_e32 v194, 16, v248
	v_and_b32_e32 v195, 0xffff0000, v248
	v_lshlrev_b32_e32 v213, 16, v249
	v_and_b32_e32 v214, 0xffff0000, v249
	v_fma_f32 v42, v194, v106, v42
	v_fma_f32 v43, v195, v107, v43
	v_fma_f32 v44, v213, v108, v44
	v_fma_f32 v45, v214, v109, v45
	v_lshlrev_b32_e32 v194, 16, v250
	v_and_b32_e32 v195, 0xffff0000, v250
	v_lshlrev_b32_e32 v213, 16, v251
	v_and_b32_e32 v214, 0xffff0000, v251
	v_fma_f32 v46, v194, v110, v46
	v_fma_f32 v47, v195, v111, v47
	v_fma_f32 v48, v213, v112, v48
	v_fma_f32 v49, v214, v113, v49
	v_lshlrev_b32_e32 v194, 16, v252
	v_and_b32_e32 v195, 0xffff0000, v252
	v_lshlrev_b32_e32 v213, 16, v253
	v_and_b32_e32 v214, 0xffff0000, v253
	v_fma_f32 v50, v194, v114, v50
	v_fma_f32 v51, v195, v115, v51
	v_fma_f32 v52, v213, v116, v52
	v_fma_f32 v53, v214, v117, v53
	v_lshlrev_b32_e32 v194, 16, v254
	v_and_b32_e32 v195, 0xffff0000, v254
	v_lshlrev_b32_e32 v213, 16, v255
	v_and_b32_e32 v214, 0xffff0000, v255
	v_fma_f32 v54, v194, v118, v54
	v_fma_f32 v55, v195, v119, v55
	v_fma_f32 v56, v213, v120, v56
	v_fma_f32 v57, v214, v121, v57
	v_lshlrev_b32_e32 v194, 16, v216
	v_and_b32_e32 v195, 0xffff0000, v216
	v_lshlrev_b32_e32 v213, 16, v217
	v_and_b32_e32 v214, 0xffff0000, v217
	v_fma_f32 v58, v194, v122, v58
	v_fma_f32 v59, v195, v123, v59
	v_fma_f32 v60, v213, v124, v60
	v_fma_f32 v61, v214, v125, v61
	v_lshlrev_b32_e32 v194, 16, v218
	v_and_b32_e32 v195, 0xffff0000, v218
	v_lshlrev_b32_e32 v213, 16, v219
	v_and_b32_e32 v214, 0xffff0000, v219
	v_fma_f32 v62, v194, v126, v62
	v_fma_f32 v63, v195, v127, v63
	v_fma_f32 v64, v213, v128, v64
	v_fma_f32 v65, v214, v129, v65
	s_add_u32 s38, s42, 0x1a81c000
	s_addc_u32 s39, s43, 0
	s_add_u32 s38, s38, s2
	s_addc_u32 s39, s39, 0
	s_nop 0
	global_load_dwordx2 v[228:229], v215, s[38:39] offset:0
	global_load_dwordx2 v[230:231], v215, s[38:39] offset:32
	global_load_dwordx2 v[232:233], v215, s[38:39] offset:64
	global_load_dwordx2 v[234:235], v215, s[38:39] offset:96
	global_load_dwordx2 v[236:237], v220, s[38:39] offset:0
	global_load_dwordx2 v[238:239], v220, s[38:39] offset:32
	global_load_dwordx2 v[240:241], v220, s[38:39] offset:64
	global_load_dwordx2 v[242:243], v220, s[38:39] offset:96
	global_load_dwordx2 v[244:245], v227, s[38:39] offset:0
	global_load_dwordx2 v[246:247], v227, s[38:39] offset:32
	global_load_dwordx2 v[248:249], v227, s[38:39] offset:64
	global_load_dwordx2 v[250:251], v227, s[38:39] offset:96
	global_load_dwordx2 v[252:253], v0, s[38:39] offset:0
	global_load_dwordx2 v[254:255], v0, s[38:39] offset:32
	global_load_dwordx2 v[216:217], v0, s[38:39] offset:64
	global_load_dwordx2 v[218:219], v0, s[38:39] offset:96
	v_mul_f32_e32 v130, 0xbfb8aa3b, v130
	v_mul_f32_e32 v131, 0xbfb8aa3b, v131
	v_mul_f32_e32 v132, 0xbfb8aa3b, v132
	v_mul_f32_e32 v133, 0xbfb8aa3b, v133
	v_exp_f32_e32 v130, v130
	v_exp_f32_e32 v131, v131
	v_exp_f32_e32 v132, v132
	v_exp_f32_e32 v133, v133
	v_add_f32_e32 v130, 1.0, v130
	v_add_f32_e32 v131, 1.0, v131
	v_add_f32_e32 v132, 1.0, v132
	v_add_f32_e32 v133, 1.0, v133
	v_rcp_f32_e32 v130, v130
	v_rcp_f32_e32 v131, v131
	v_rcp_f32_e32 v132, v132
	v_rcp_f32_e32 v133, v133
	v_mul_f32_e32 v134, 0xbfb8aa3b, v134
	v_mul_f32_e32 v135, 0xbfb8aa3b, v135
	v_mul_f32_e32 v136, 0xbfb8aa3b, v136
	v_mul_f32_e32 v137, 0xbfb8aa3b, v137
	v_exp_f32_e32 v134, v134
	v_exp_f32_e32 v135, v135
	v_exp_f32_e32 v136, v136
	v_exp_f32_e32 v137, v137
	v_add_f32_e32 v134, 1.0, v134
	v_add_f32_e32 v135, 1.0, v135
	v_add_f32_e32 v136, 1.0, v136
	v_add_f32_e32 v137, 1.0, v137
	v_rcp_f32_e32 v134, v134
	v_rcp_f32_e32 v135, v135
	v_rcp_f32_e32 v136, v136
	v_rcp_f32_e32 v137, v137
	v_mul_f32_e32 v138, 0xbfb8aa3b, v138
	v_mul_f32_e32 v139, 0xbfb8aa3b, v139
	v_mul_f32_e32 v140, 0xbfb8aa3b, v140
	v_mul_f32_e32 v141, 0xbfb8aa3b, v141
	v_exp_f32_e32 v138, v138
	v_exp_f32_e32 v139, v139
	v_exp_f32_e32 v140, v140
	v_exp_f32_e32 v141, v141
	v_add_f32_e32 v138, 1.0, v138
	v_add_f32_e32 v139, 1.0, v139
	v_add_f32_e32 v140, 1.0, v140
	v_add_f32_e32 v141, 1.0, v141
	v_rcp_f32_e32 v138, v138
	v_rcp_f32_e32 v139, v139
	v_rcp_f32_e32 v140, v140
	v_rcp_f32_e32 v141, v141
	v_mul_f32_e32 v142, 0xbfb8aa3b, v142
	v_mul_f32_e32 v143, 0xbfb8aa3b, v143
	v_mul_f32_e32 v144, 0xbfb8aa3b, v144
	v_mul_f32_e32 v145, 0xbfb8aa3b, v145
	v_exp_f32_e32 v142, v142
	v_exp_f32_e32 v143, v143
	v_exp_f32_e32 v144, v144
	v_exp_f32_e32 v145, v145
	v_add_f32_e32 v142, 1.0, v142
	v_add_f32_e32 v143, 1.0, v143
	v_add_f32_e32 v144, 1.0, v144
	v_add_f32_e32 v145, 1.0, v145
	v_rcp_f32_e32 v142, v142
	v_rcp_f32_e32 v143, v143
	v_rcp_f32_e32 v144, v144
	v_rcp_f32_e32 v145, v145
	v_mul_f32_e32 v146, 0xbfb8aa3b, v146
	v_mul_f32_e32 v147, 0xbfb8aa3b, v147
	v_mul_f32_e32 v148, 0xbfb8aa3b, v148
	v_mul_f32_e32 v149, 0xbfb8aa3b, v149
	v_exp_f32_e32 v146, v146
	v_exp_f32_e32 v147, v147
	v_exp_f32_e32 v148, v148
	v_exp_f32_e32 v149, v149
	v_add_f32_e32 v146, 1.0, v146
	v_add_f32_e32 v147, 1.0, v147
	v_add_f32_e32 v148, 1.0, v148
	v_add_f32_e32 v149, 1.0, v149
	v_rcp_f32_e32 v146, v146
	v_rcp_f32_e32 v147, v147
	v_rcp_f32_e32 v148, v148
	v_rcp_f32_e32 v149, v149
	v_mul_f32_e32 v150, 0xbfb8aa3b, v150
	v_mul_f32_e32 v151, 0xbfb8aa3b, v151
	v_mul_f32_e32 v152, 0xbfb8aa3b, v152
	v_mul_f32_e32 v153, 0xbfb8aa3b, v153
	v_exp_f32_e32 v150, v150
	v_exp_f32_e32 v151, v151
	v_exp_f32_e32 v152, v152
	v_exp_f32_e32 v153, v153
	v_add_f32_e32 v150, 1.0, v150
	v_add_f32_e32 v151, 1.0, v151
	v_add_f32_e32 v152, 1.0, v152
	v_add_f32_e32 v153, 1.0, v153
	v_rcp_f32_e32 v150, v150
	v_rcp_f32_e32 v151, v151
	v_rcp_f32_e32 v152, v152
	v_rcp_f32_e32 v153, v153
	v_mul_f32_e32 v154, 0xbfb8aa3b, v154
	v_mul_f32_e32 v155, 0xbfb8aa3b, v155
	v_mul_f32_e32 v156, 0xbfb8aa3b, v156
	v_mul_f32_e32 v157, 0xbfb8aa3b, v157
	v_exp_f32_e32 v154, v154
	v_exp_f32_e32 v155, v155
	v_exp_f32_e32 v156, v156
	v_exp_f32_e32 v157, v157
	v_add_f32_e32 v154, 1.0, v154
	v_add_f32_e32 v155, 1.0, v155
	v_add_f32_e32 v156, 1.0, v156
	v_add_f32_e32 v157, 1.0, v157
	v_rcp_f32_e32 v154, v154
	v_rcp_f32_e32 v155, v155
	v_rcp_f32_e32 v156, v156
	v_rcp_f32_e32 v157, v157
	v_mul_f32_e32 v158, 0xbfb8aa3b, v158
	v_mul_f32_e32 v159, 0xbfb8aa3b, v159
	v_mul_f32_e32 v160, 0xbfb8aa3b, v160
	v_mul_f32_e32 v161, 0xbfb8aa3b, v161
	v_exp_f32_e32 v158, v158
	v_exp_f32_e32 v159, v159
	v_exp_f32_e32 v160, v160
	v_exp_f32_e32 v161, v161
	v_add_f32_e32 v158, 1.0, v158
	v_add_f32_e32 v159, 1.0, v159
	v_add_f32_e32 v160, 1.0, v160
	v_add_f32_e32 v161, 1.0, v161
	v_rcp_f32_e32 v158, v158
	v_rcp_f32_e32 v159, v159
	v_rcp_f32_e32 v160, v160
	v_rcp_f32_e32 v161, v161
	v_mul_f32_e32 v162, 0xbfb8aa3b, v162
	v_mul_f32_e32 v163, 0xbfb8aa3b, v163
	v_mul_f32_e32 v164, 0xbfb8aa3b, v164
	v_mul_f32_e32 v165, 0xbfb8aa3b, v165
	v_exp_f32_e32 v162, v162
	v_exp_f32_e32 v163, v163
	v_exp_f32_e32 v164, v164
	v_exp_f32_e32 v165, v165
	v_add_f32_e32 v162, 1.0, v162
	v_add_f32_e32 v163, 1.0, v163
	v_add_f32_e32 v164, 1.0, v164
	v_add_f32_e32 v165, 1.0, v165
	v_rcp_f32_e32 v162, v162
	v_rcp_f32_e32 v163, v163
	v_rcp_f32_e32 v164, v164
	v_rcp_f32_e32 v165, v165
	v_mul_f32_e32 v166, 0xbfb8aa3b, v166
	v_mul_f32_e32 v167, 0xbfb8aa3b, v167
	v_mul_f32_e32 v168, 0xbfb8aa3b, v168
	v_mul_f32_e32 v169, 0xbfb8aa3b, v169
	v_exp_f32_e32 v166, v166
	v_exp_f32_e32 v167, v167
	v_exp_f32_e32 v168, v168
	v_exp_f32_e32 v169, v169
	v_add_f32_e32 v166, 1.0, v166
	v_add_f32_e32 v167, 1.0, v167
	v_add_f32_e32 v168, 1.0, v168
	v_add_f32_e32 v169, 1.0, v169
	v_rcp_f32_e32 v166, v166
	v_rcp_f32_e32 v167, v167
	v_rcp_f32_e32 v168, v168
	v_rcp_f32_e32 v169, v169
	v_mul_f32_e32 v170, 0xbfb8aa3b, v170
	v_mul_f32_e32 v171, 0xbfb8aa3b, v171
	v_mul_f32_e32 v172, 0xbfb8aa3b, v172
	v_mul_f32_e32 v173, 0xbfb8aa3b, v173
	v_exp_f32_e32 v170, v170
	v_exp_f32_e32 v171, v171
	v_exp_f32_e32 v172, v172
	v_exp_f32_e32 v173, v173
	v_add_f32_e32 v170, 1.0, v170
	v_add_f32_e32 v171, 1.0, v171
	v_add_f32_e32 v172, 1.0, v172
	v_add_f32_e32 v173, 1.0, v173
	v_rcp_f32_e32 v170, v170
	v_rcp_f32_e32 v171, v171
	v_rcp_f32_e32 v172, v172
	v_rcp_f32_e32 v173, v173
	v_mul_f32_e32 v174, 0xbfb8aa3b, v174
	v_mul_f32_e32 v175, 0xbfb8aa3b, v175
	v_mul_f32_e32 v176, 0xbfb8aa3b, v176
	v_mul_f32_e32 v177, 0xbfb8aa3b, v177
	v_exp_f32_e32 v174, v174
	v_exp_f32_e32 v175, v175
	v_exp_f32_e32 v176, v176
	v_exp_f32_e32 v177, v177
	v_add_f32_e32 v174, 1.0, v174
	v_add_f32_e32 v175, 1.0, v175
	v_add_f32_e32 v176, 1.0, v176
	v_add_f32_e32 v177, 1.0, v177
	v_rcp_f32_e32 v174, v174
	v_rcp_f32_e32 v175, v175
	v_rcp_f32_e32 v176, v176
	v_rcp_f32_e32 v177, v177
	v_mul_f32_e32 v178, 0xbfb8aa3b, v178
	v_mul_f32_e32 v179, 0xbfb8aa3b, v179
	v_mul_f32_e32 v180, 0xbfb8aa3b, v180
	v_mul_f32_e32 v181, 0xbfb8aa3b, v181
	v_exp_f32_e32 v178, v178
	v_exp_f32_e32 v179, v179
	v_exp_f32_e32 v180, v180
	v_exp_f32_e32 v181, v181
	v_add_f32_e32 v178, 1.0, v178
	v_add_f32_e32 v179, 1.0, v179
	v_add_f32_e32 v180, 1.0, v180
	v_add_f32_e32 v181, 1.0, v181
	v_rcp_f32_e32 v178, v178
	v_rcp_f32_e32 v179, v179
	v_rcp_f32_e32 v180, v180
	v_rcp_f32_e32 v181, v181
	v_mul_f32_e32 v182, 0xbfb8aa3b, v182
	v_mul_f32_e32 v183, 0xbfb8aa3b, v183
	v_mul_f32_e32 v184, 0xbfb8aa3b, v184
	v_mul_f32_e32 v185, 0xbfb8aa3b, v185
	v_exp_f32_e32 v182, v182
	v_exp_f32_e32 v183, v183
	v_exp_f32_e32 v184, v184
	v_exp_f32_e32 v185, v185
	v_add_f32_e32 v182, 1.0, v182
	v_add_f32_e32 v183, 1.0, v183
	v_add_f32_e32 v184, 1.0, v184
	v_add_f32_e32 v185, 1.0, v185
	v_rcp_f32_e32 v182, v182
	v_rcp_f32_e32 v183, v183
	v_rcp_f32_e32 v184, v184
	v_rcp_f32_e32 v185, v185
	v_mul_f32_e32 v186, 0xbfb8aa3b, v186
	v_mul_f32_e32 v187, 0xbfb8aa3b, v187
	v_mul_f32_e32 v188, 0xbfb8aa3b, v188
	v_mul_f32_e32 v189, 0xbfb8aa3b, v189
	v_exp_f32_e32 v186, v186
	v_exp_f32_e32 v187, v187
	v_exp_f32_e32 v188, v188
	v_exp_f32_e32 v189, v189
	v_add_f32_e32 v186, 1.0, v186
	v_add_f32_e32 v187, 1.0, v187
	v_add_f32_e32 v188, 1.0, v188
	v_add_f32_e32 v189, 1.0, v189
	v_rcp_f32_e32 v186, v186
	v_rcp_f32_e32 v187, v187
	v_rcp_f32_e32 v188, v188
	v_rcp_f32_e32 v189, v189
	v_mul_f32_e32 v190, 0xbfb8aa3b, v190
	v_mul_f32_e32 v191, 0xbfb8aa3b, v191
	v_mul_f32_e32 v192, 0xbfb8aa3b, v192
	v_mul_f32_e32 v193, 0xbfb8aa3b, v193
	v_exp_f32_e32 v190, v190
	v_exp_f32_e32 v191, v191
	v_exp_f32_e32 v192, v192
	v_exp_f32_e32 v193, v193
	v_add_f32_e32 v190, 1.0, v190
	v_add_f32_e32 v191, 1.0, v191
	v_add_f32_e32 v192, 1.0, v192
	v_add_f32_e32 v193, 1.0, v193
	v_rcp_f32_e32 v190, v190
	v_rcp_f32_e32 v191, v191
	v_rcp_f32_e32 v192, v192
	v_rcp_f32_e32 v193, v193
	s_waitcnt vmcnt(0)
	v_lshlrev_b32_e32 v194, 16, v228
	v_and_b32_e32 v195, 0xffff0000, v228
	v_lshlrev_b32_e32 v213, 16, v229
	v_and_b32_e32 v214, 0xffff0000, v229
	v_fma_f32 v2, v194, v130, v2
	v_fma_f32 v3, v195, v131, v3
	v_fma_f32 v4, v213, v132, v4
	v_fma_f32 v5, v214, v133, v5
	v_lshlrev_b32_e32 v194, 16, v230
	v_and_b32_e32 v195, 0xffff0000, v230
	v_lshlrev_b32_e32 v213, 16, v231
	v_and_b32_e32 v214, 0xffff0000, v231
	v_fma_f32 v6, v194, v134, v6
	v_fma_f32 v7, v195, v135, v7
	v_fma_f32 v8, v213, v136, v8
	v_fma_f32 v9, v214, v137, v9
	v_lshlrev_b32_e32 v194, 16, v232
	v_and_b32_e32 v195, 0xffff0000, v232
	v_lshlrev_b32_e32 v213, 16, v233
	v_and_b32_e32 v214, 0xffff0000, v233
	v_fma_f32 v10, v194, v138, v10
	v_fma_f32 v11, v195, v139, v11
	v_fma_f32 v12, v213, v140, v12
	v_fma_f32 v13, v214, v141, v13
	v_lshlrev_b32_e32 v194, 16, v234
	v_and_b32_e32 v195, 0xffff0000, v234
	v_lshlrev_b32_e32 v213, 16, v235
	v_and_b32_e32 v214, 0xffff0000, v235
	v_fma_f32 v14, v194, v142, v14
	v_fma_f32 v15, v195, v143, v15
	v_fma_f32 v16, v213, v144, v16
	v_fma_f32 v17, v214, v145, v17
	v_lshlrev_b32_e32 v194, 16, v236
	v_and_b32_e32 v195, 0xffff0000, v236
	v_lshlrev_b32_e32 v213, 16, v237
	v_and_b32_e32 v214, 0xffff0000, v237
	v_fma_f32 v18, v194, v146, v18
	v_fma_f32 v19, v195, v147, v19
	v_fma_f32 v20, v213, v148, v20
	v_fma_f32 v21, v214, v149, v21
	v_lshlrev_b32_e32 v194, 16, v238
	v_and_b32_e32 v195, 0xffff0000, v238
	v_lshlrev_b32_e32 v213, 16, v239
	v_and_b32_e32 v214, 0xffff0000, v239
	v_fma_f32 v22, v194, v150, v22
	v_fma_f32 v23, v195, v151, v23
	v_fma_f32 v24, v213, v152, v24
	v_fma_f32 v25, v214, v153, v25
	v_lshlrev_b32_e32 v194, 16, v240
	v_and_b32_e32 v195, 0xffff0000, v240
	v_lshlrev_b32_e32 v213, 16, v241
	v_and_b32_e32 v214, 0xffff0000, v241
	v_fma_f32 v26, v194, v154, v26
	v_fma_f32 v27, v195, v155, v27
	v_fma_f32 v28, v213, v156, v28
	v_fma_f32 v29, v214, v157, v29
	v_lshlrev_b32_e32 v194, 16, v242
	v_and_b32_e32 v195, 0xffff0000, v242
	v_lshlrev_b32_e32 v213, 16, v243
	v_and_b32_e32 v214, 0xffff0000, v243
	v_fma_f32 v30, v194, v158, v30
	v_fma_f32 v31, v195, v159, v31
	v_fma_f32 v32, v213, v160, v32
	v_fma_f32 v33, v214, v161, v33
	v_lshlrev_b32_e32 v194, 16, v244
	v_and_b32_e32 v195, 0xffff0000, v244
	v_lshlrev_b32_e32 v213, 16, v245
	v_and_b32_e32 v214, 0xffff0000, v245
	v_fma_f32 v34, v194, v162, v34
	v_fma_f32 v35, v195, v163, v35
	v_fma_f32 v36, v213, v164, v36
	v_fma_f32 v37, v214, v165, v37
	v_lshlrev_b32_e32 v194, 16, v246
	v_and_b32_e32 v195, 0xffff0000, v246
	v_lshlrev_b32_e32 v213, 16, v247
	v_and_b32_e32 v214, 0xffff0000, v247
	v_fma_f32 v38, v194, v166, v38
	v_fma_f32 v39, v195, v167, v39
	v_fma_f32 v40, v213, v168, v40
	v_fma_f32 v41, v214, v169, v41
	v_lshlrev_b32_e32 v194, 16, v248
	v_and_b32_e32 v195, 0xffff0000, v248
	v_lshlrev_b32_e32 v213, 16, v249
	v_and_b32_e32 v214, 0xffff0000, v249
	v_fma_f32 v42, v194, v170, v42
	v_fma_f32 v43, v195, v171, v43
	v_fma_f32 v44, v213, v172, v44
	v_fma_f32 v45, v214, v173, v45
	v_lshlrev_b32_e32 v194, 16, v250
	v_and_b32_e32 v195, 0xffff0000, v250
	v_lshlrev_b32_e32 v213, 16, v251
	v_and_b32_e32 v214, 0xffff0000, v251
	v_fma_f32 v46, v194, v174, v46
	v_fma_f32 v47, v195, v175, v47
	v_fma_f32 v48, v213, v176, v48
	v_fma_f32 v49, v214, v177, v49
	v_lshlrev_b32_e32 v194, 16, v252
	v_and_b32_e32 v195, 0xffff0000, v252
	v_lshlrev_b32_e32 v213, 16, v253
	v_and_b32_e32 v214, 0xffff0000, v253
	v_fma_f32 v50, v194, v178, v50
	v_fma_f32 v51, v195, v179, v51
	v_fma_f32 v52, v213, v180, v52
	v_fma_f32 v53, v214, v181, v53
	v_lshlrev_b32_e32 v194, 16, v254
	v_and_b32_e32 v195, 0xffff0000, v254
	v_lshlrev_b32_e32 v213, 16, v255
	v_and_b32_e32 v214, 0xffff0000, v255
	v_fma_f32 v54, v194, v182, v54
	v_fma_f32 v55, v195, v183, v55
	v_fma_f32 v56, v213, v184, v56
	v_fma_f32 v57, v214, v185, v57
	v_lshlrev_b32_e32 v194, 16, v216
	v_and_b32_e32 v195, 0xffff0000, v216
	v_lshlrev_b32_e32 v213, 16, v217
	v_and_b32_e32 v214, 0xffff0000, v217
	v_fma_f32 v58, v194, v186, v58
	v_fma_f32 v59, v195, v187, v59
	v_fma_f32 v60, v213, v188, v60
	v_fma_f32 v61, v214, v189, v61
	v_lshlrev_b32_e32 v194, 16, v218
	v_and_b32_e32 v195, 0xffff0000, v218
	v_lshlrev_b32_e32 v213, 16, v219
	v_and_b32_e32 v214, 0xffff0000, v219
	v_fma_f32 v62, v194, v190, v62
	v_fma_f32 v63, v195, v191, v63
	v_fma_f32 v64, v213, v192, v64
	v_fma_f32 v65, v214, v193, v65
	v_and_b32_e32 v213, 15, v196
	v_lshrrev_b32_e32 v220, 7, v196
	v_lshl_add_u32 v213, v220, 6, v213
	v_mul_u32_u24_e32 v213, 0x110, v213
	v_bfe_u32 v220, v196, 6, 1
	v_lshl_add_u32 v213, v220, 7, v213
	v_bfe_u32 v220, v196, 4, 2
	v_lshl_add_u32 v213, v220, 3, v213
	v_cvt_pk_bf16_f32 v194, v2, v3
	v_cvt_pk_bf16_f32 v195, v4, v5
	ds_write_b64 v213, v[194:195] offset:0
	v_cvt_pk_bf16_f32 v214, v6, v7
	v_cvt_pk_bf16_f32 v215, v8, v9
	ds_write_b64 v213, v[214:215] offset:32
	v_cvt_pk_bf16_f32 v194, v10, v11
	v_cvt_pk_bf16_f32 v195, v12, v13
	ds_write_b64 v213, v[194:195] offset:64
	v_cvt_pk_bf16_f32 v214, v14, v15
	v_cvt_pk_bf16_f32 v215, v16, v17
	ds_write_b64 v213, v[214:215] offset:96
	v_cvt_pk_bf16_f32 v194, v18, v19
	v_cvt_pk_bf16_f32 v195, v20, v21
	ds_write_b64 v213, v[194:195] offset:4352
	v_cvt_pk_bf16_f32 v214, v22, v23
	v_cvt_pk_bf16_f32 v215, v24, v25
	ds_write_b64 v213, v[214:215] offset:4384
	v_cvt_pk_bf16_f32 v194, v26, v27
	v_cvt_pk_bf16_f32 v195, v28, v29
	ds_write_b64 v213, v[194:195] offset:4416
	v_cvt_pk_bf16_f32 v214, v30, v31
	v_cvt_pk_bf16_f32 v215, v32, v33
	ds_write_b64 v213, v[214:215] offset:4448
	v_cvt_pk_bf16_f32 v194, v34, v35
	v_cvt_pk_bf16_f32 v195, v36, v37
	ds_write_b64 v213, v[194:195] offset:8704
	v_cvt_pk_bf16_f32 v214, v38, v39
	v_cvt_pk_bf16_f32 v215, v40, v41
	ds_write_b64 v213, v[214:215] offset:8736
	v_cvt_pk_bf16_f32 v194, v42, v43
	v_cvt_pk_bf16_f32 v195, v44, v45
	ds_write_b64 v213, v[194:195] offset:8768
	v_cvt_pk_bf16_f32 v214, v46, v47
	v_cvt_pk_bf16_f32 v215, v48, v49
	ds_write_b64 v213, v[214:215] offset:8800
	v_cvt_pk_bf16_f32 v194, v50, v51
	v_cvt_pk_bf16_f32 v195, v52, v53
	ds_write_b64 v213, v[194:195] offset:13056
	v_cvt_pk_bf16_f32 v214, v54, v55
	v_cvt_pk_bf16_f32 v215, v56, v57
	ds_write_b64 v213, v[214:215] offset:13088
	v_cvt_pk_bf16_f32 v194, v58, v59
	v_cvt_pk_bf16_f32 v195, v60, v61
	ds_write_b64 v213, v[194:195] offset:13120
	v_cvt_pk_bf16_f32 v214, v62, v63
	v_cvt_pk_bf16_f32 v215, v64, v65
	ds_write_b64 v213, v[214:215] offset:13152
	v_lshrrev_b32_e32 v220, 4, v196
	v_and_b32_e32 v0, 15, v196
	v_lshlrev_b32_e32 v0, 4, v0
	v_lshl_add_u32 v227, v220, 11, v0
	v_mad_u32_u24 v220, v220, s30, v0
	s_add_u32 s38, s19, s2
	s_addc_u32 s39, s20, 0
	s_waitcnt lgkmcnt(0)
	s_barrier
	ds_read_b128 v[228:231], v220 offset:0
	ds_read_b128 v[232:235], v220 offset:4352
	ds_read_b128 v[236:239], v220 offset:8704
	ds_read_b128 v[240:243], v220 offset:13056
	ds_read_b128 v[244:247], v220 offset:17408
	ds_read_b128 v[248:251], v220 offset:21760
	ds_read_b128 v[252:255], v220 offset:26112
	ds_read_b128 v[216:219], v220 offset:30464
	s_waitcnt lgkmcnt(7)
	global_store_dwordx4 v227, v[228:231], s[38:39]
	v_add_u32_e32 v227, 0x8000, v227
	s_waitcnt lgkmcnt(6)
	global_store_dwordx4 v227, v[232:235], s[38:39]
	v_add_u32_e32 v227, 0x8000, v227
	s_waitcnt lgkmcnt(5)
	global_store_dwordx4 v227, v[236:239], s[38:39]
	v_add_u32_e32 v227, 0x8000, v227
	s_waitcnt lgkmcnt(4)
	global_store_dwordx4 v227, v[240:243], s[38:39]
	v_add_u32_e32 v227, 0x8000, v227
	s_waitcnt lgkmcnt(3)
	global_store_dwordx4 v227, v[244:247], s[38:39]
	v_add_u32_e32 v227, 0x8000, v227
	s_waitcnt lgkmcnt(2)
	global_store_dwordx4 v227, v[248:251], s[38:39]
	v_add_u32_e32 v227, 0x8000, v227
	s_waitcnt lgkmcnt(1)
	global_store_dwordx4 v227, v[252:255], s[38:39]
	v_add_u32_e32 v227, 0x8000, v227
	s_waitcnt lgkmcnt(0)
	global_store_dwordx4 v227, v[216:219], s[38:39]
	s_barrier
	v_readlane_b32 s0, v225, 42
	v_readlane_b32 s1, v225, 43
	s_load_dword s0, s[0:1], 0x0
	s_waitcnt lgkmcnt(0)
	s_add_i32 s24, s0, s24
	s_cmp_ge_i32 s24, s14
	s_cbranch_scc0 .LBB0_189
